# P2 mixer loop: pool_scale loads issued first and the pre-epilogue full drain replaced by counted waits (spatial operands waited right before their first MFMA)
# baseline (speedup 1.0000x reference)
.LBB0_313:
	ds_read_b128 v[104:107], v241 offset:36864
	ds_read_b128 v[112:115], v241 offset:36928
	s_lshl_b32 s14, s40, 1
	s_add_i32 s14, s14, s11
	s_lshl_b32 s22, s14, 7
	s_waitcnt vmcnt(15) lgkmcnt(1)
	v_mfma_f32_16x16x32_bf16 v[108:111], v[84:87], v[104:107], 0
	v_or_b32_e32 v10, s22, v233
	v_mov_b32_e32 v11, v8
	v_readlane_b32 s72, v249, 32
	s_waitcnt vmcnt(11)
	v_mfma_f32_16x16x32_bf16 v[104:107], v[100:103], v[104:107], 0
	v_readlane_b32 s73, v249, 33
	v_readlane_b32 s74, v249, 34
	v_readlane_b32 s75, v249, 35
	s_waitcnt lgkmcnt(0)
	v_mfma_f32_16x16x32_bf16 v[108:111], v[80:83], v[112:115], v[108:111]
	v_readlane_b32 s76, v249, 36
	v_readlane_b32 s77, v249, 37
	v_readlane_b32 s78, v249, 38
	s_waitcnt vmcnt(10)
	v_mfma_f32_16x16x32_bf16 v[104:107], v[96:99], v[112:115], v[104:107]
	ds_read_b128 v[112:115], v241 offset:36992
	v_readlane_b32 s79, v249, 39
	v_readlane_b32 s80, v249, 40
	s_waitcnt lgkmcnt(0)
	v_mfma_f32_16x16x32_bf16 v[108:111], v[76:79], v[112:115], v[108:111]
	v_readlane_b32 s81, v249, 41
	v_readlane_b32 s82, v249, 42
	v_readlane_b32 s83, v249, 43
	s_waitcnt vmcnt(9)
	v_mfma_f32_16x16x32_bf16 v[104:107], v[92:95], v[112:115], v[104:107]
	ds_read_b128 v[112:115], v241 offset:37056
	v_readlane_b32 s84, v249, 44
	v_readlane_b32 s85, v249, 45
	s_waitcnt vmcnt(8) lgkmcnt(0)
	v_mfma_f32_16x16x32_bf16 v[184:187], v[88:91], v[112:115], v[104:107]
	v_readlane_b32 s86, v249, 46
	s_nop 1
	ds_read_b128 v[104:107], v241 offset:41216
	v_readlane_b32 s87, v249, 47
	v_mfma_f32_16x16x32_bf16 v[188:191], v[72:75], v[112:115], v[108:111]
	ds_read_b128 v[112:115], v241 offset:41280
	v_or_b32_e32 v216, s3, v233
	v_or_b32_e32 v9, s3, v234
	s_waitcnt lgkmcnt(1)
	v_mfma_f32_16x16x32_bf16 v[108:111], v[84:87], v[104:107], 0
	v_mov_b32_e32 v199, v8
	v_ashrrev_i32_e32 v217, 31, v216
	v_mfma_f32_16x16x32_bf16 v[104:107], v[100:103], v[104:107], 0
	s_waitcnt lgkmcnt(0)
	v_mfma_f32_16x16x32_bf16 v[108:111], v[80:83], v[112:115], v[108:111]
	v_mfma_f32_16x16x32_bf16 v[104:107], v[96:99], v[112:115], v[104:107]
	ds_read_b128 v[112:115], v241 offset:41344
	s_waitcnt lgkmcnt(0)
	v_mfma_f32_16x16x32_bf16 v[108:111], v[76:79], v[112:115], v[108:111]
	v_mfma_f32_16x16x32_bf16 v[104:107], v[92:95], v[112:115], v[104:107]
	ds_read_b128 v[112:115], v241 offset:41408
	s_waitcnt lgkmcnt(0)
	v_mfma_f32_16x16x32_bf16 v[168:171], v[88:91], v[112:115], v[104:107]
	s_nop 4
	ds_read_b128 v[104:107], v241 offset:45568
	v_mfma_f32_16x16x32_bf16 v[172:175], v[72:75], v[112:115], v[108:111]
	ds_read_b128 v[112:115], v241 offset:45632
	s_waitcnt lgkmcnt(1)
	v_mfma_f32_16x16x32_bf16 v[108:111], v[84:87], v[104:107], 0
	v_mfma_f32_16x16x32_bf16 v[104:107], v[100:103], v[104:107], 0
	s_waitcnt lgkmcnt(0)
	v_mfma_f32_16x16x32_bf16 v[108:111], v[80:83], v[112:115], v[108:111]
	v_mfma_f32_16x16x32_bf16 v[104:107], v[96:99], v[112:115], v[104:107]
	ds_read_b128 v[112:115], v241 offset:45696
	s_waitcnt lgkmcnt(0)
	v_mfma_f32_16x16x32_bf16 v[108:111], v[76:79], v[112:115], v[108:111]
	v_mfma_f32_16x16x32_bf16 v[104:107], v[92:95], v[112:115], v[104:107]
	ds_read_b128 v[112:115], v241 offset:45760
	s_waitcnt lgkmcnt(0)
	v_mfma_f32_16x16x32_bf16 v[160:163], v[88:91], v[112:115], v[104:107]
	s_nop 4
	ds_read_b128 v[104:107], v242 offset:36864
	v_mfma_f32_16x16x32_bf16 v[164:167], v[72:75], v[112:115], v[108:111]
	ds_read_b128 v[112:115], v242 offset:36928
	s_waitcnt lgkmcnt(1)
	v_mfma_f32_16x16x32_bf16 v[108:111], v[84:87], v[104:107], 0
	v_mfma_f32_16x16x32_bf16 v[104:107], v[100:103], v[104:107], 0
	s_waitcnt lgkmcnt(0)
	v_mfma_f32_16x16x32_bf16 v[108:111], v[80:83], v[112:115], v[108:111]
	v_mfma_f32_16x16x32_bf16 v[104:107], v[96:99], v[112:115], v[104:107]
	ds_read_b128 v[112:115], v242 offset:36992
	s_waitcnt lgkmcnt(0)
	v_mfma_f32_16x16x32_bf16 v[108:111], v[76:79], v[112:115], v[108:111]
	v_mfma_f32_16x16x32_bf16 v[104:107], v[92:95], v[112:115], v[104:107]
	ds_read_b128 v[112:115], v242 offset:37056
	s_waitcnt lgkmcnt(0)
	v_mfma_f32_16x16x32_bf16 v[152:155], v[88:91], v[112:115], v[104:107]
	s_nop 4
	ds_read_b128 v[104:107], v241 offset:54272
	v_mfma_f32_16x16x32_bf16 v[156:159], v[72:75], v[112:115], v[108:111]
	ds_read_b128 v[112:115], v241 offset:54336
	s_waitcnt lgkmcnt(1)
	v_mfma_f32_16x16x32_bf16 v[108:111], v[84:87], v[104:107], 0
	v_mfma_f32_16x16x32_bf16 v[104:107], v[100:103], v[104:107], 0
	s_waitcnt lgkmcnt(0)
	v_mfma_f32_16x16x32_bf16 v[108:111], v[80:83], v[112:115], v[108:111]
	v_mfma_f32_16x16x32_bf16 v[104:107], v[96:99], v[112:115], v[104:107]
	ds_read_b128 v[112:115], v241 offset:54400
	s_waitcnt lgkmcnt(0)
	v_mfma_f32_16x16x32_bf16 v[108:111], v[76:79], v[112:115], v[108:111]
	v_mfma_f32_16x16x32_bf16 v[104:107], v[92:95], v[112:115], v[104:107]
	ds_read_b128 v[112:115], v241 offset:54464
	s_waitcnt lgkmcnt(0)
	v_mfma_f32_16x16x32_bf16 v[144:147], v[88:91], v[112:115], v[104:107]
	s_nop 4
	ds_read_b128 v[104:107], v241 offset:58624
	v_mfma_f32_16x16x32_bf16 v[148:151], v[72:75], v[112:115], v[108:111]
	ds_read_b128 v[112:115], v241 offset:58688
	s_waitcnt lgkmcnt(1)
	v_mfma_f32_16x16x32_bf16 v[108:111], v[84:87], v[104:107], 0
	v_mfma_f32_16x16x32_bf16 v[104:107], v[100:103], v[104:107], 0
	s_waitcnt lgkmcnt(0)
	v_mfma_f32_16x16x32_bf16 v[108:111], v[80:83], v[112:115], v[108:111]
	v_mfma_f32_16x16x32_bf16 v[104:107], v[96:99], v[112:115], v[104:107]
	ds_read_b128 v[112:115], v241 offset:58752
	s_waitcnt lgkmcnt(0)
	v_mfma_f32_16x16x32_bf16 v[108:111], v[76:79], v[112:115], v[108:111]
	v_mfma_f32_16x16x32_bf16 v[104:107], v[92:95], v[112:115], v[104:107]
	ds_read_b128 v[112:115], v241 offset:58816
	s_waitcnt lgkmcnt(0)
	v_mfma_f32_16x16x32_bf16 v[136:139], v[88:91], v[112:115], v[104:107]
	s_nop 4
	ds_read_b128 v[104:107], v241 offset:62976
	v_mfma_f32_16x16x32_bf16 v[140:143], v[72:75], v[112:115], v[108:111]
	ds_read_b128 v[112:115], v241 offset:63040
	s_waitcnt lgkmcnt(1)
	v_mfma_f32_16x16x32_bf16 v[108:111], v[84:87], v[104:107], 0
	v_mfma_f32_16x16x32_bf16 v[104:107], v[100:103], v[104:107], 0
	s_waitcnt lgkmcnt(0)
	v_mfma_f32_16x16x32_bf16 v[108:111], v[80:83], v[112:115], v[108:111]
	v_mfma_f32_16x16x32_bf16 v[104:107], v[96:99], v[112:115], v[104:107]
	ds_read_b128 v[112:115], v241 offset:63104
	s_waitcnt lgkmcnt(0)
	v_mfma_f32_16x16x32_bf16 v[108:111], v[76:79], v[112:115], v[108:111]
	v_mfma_f32_16x16x32_bf16 v[104:107], v[92:95], v[112:115], v[104:107]
	ds_read_b128 v[112:115], v241 offset:63168
	s_waitcnt lgkmcnt(0)
	v_mfma_f32_16x16x32_bf16 v[128:131], v[88:91], v[112:115], v[104:107]
	s_nop 4
	ds_read_b128 v[104:107], v243 offset:36864
	s_waitcnt lgkmcnt(0)
	v_mfma_f32_16x16x32_bf16 v[84:87], v[84:87], v[104:107], 0
	v_mfma_f32_16x16x32_bf16 v[100:103], v[100:103], v[104:107], 0
	ds_read_b128 v[104:107], v243 offset:36928
	s_waitcnt lgkmcnt(0)
	v_mfma_f32_16x16x32_bf16 v[80:83], v[80:83], v[104:107], v[84:87]
	v_mfma_f32_16x16x32_bf16 v[84:87], v[96:99], v[104:107], v[100:103]
	ds_read_b128 v[96:99], v243 offset:36992
	s_waitcnt lgkmcnt(0)
	v_mfma_f32_16x16x32_bf16 v[76:79], v[76:79], v[96:99], v[80:83]
	v_mfma_f32_16x16x32_bf16 v[80:83], v[92:95], v[96:99], v[84:87]
	s_nop 3
	ds_read_b128 v[84:87], v243 offset:37056
	v_mfma_f32_16x16x32_bf16 v[132:135], v[72:75], v[112:115], v[108:111]
	s_waitcnt lgkmcnt(0)
	v_mfma_f32_16x16x32_bf16 v[124:127], v[72:75], v[84:87], v[76:79]
	v_readlane_b32 s86, v249, 30
	v_readlane_b32 s87, v249, 31
	s_nop 1
	v_lshl_add_u64 v[180:181], v[220:221], 2, s[86:87]
	global_load_dwordx4 v[176:179], v[180:181], off offset:16
	s_nop 0
	global_load_dwordx4 v[180:183], v[180:181], off
	v_lshlrev_b64 v[72:73], 8, v[10:11]
	v_lshl_add_u64 v[72:73], v[196:197], 0, v[72:73]
	global_load_dwordx4 v[112:115], v[72:73], off
	global_load_dwordx4 v[100:103], v[72:73], off offset:64
	global_load_dwordx4 v[96:99], v[72:73], off offset:128
	global_load_dwordx4 v[92:95], v[72:73], off offset:192
	v_add_co_u32_e32 v72, vcc, s52, v72
	v_mfma_f32_16x16x32_bf16 v[120:123], v[88:91], v[84:87], v[80:83]
	s_nop 0
	v_addc_co_u32_e32 v73, vcc, 0, v73, vcc
	global_load_dwordx4 v[116:119], v[72:73], off
	global_load_dwordx4 v[108:111], v[72:73], off offset:64
	global_load_dwordx4 v[104:107], v[72:73], off offset:128
	global_load_dwordx4 v[88:91], v[72:73], off offset:192
	v_mov_b64_e32 v[72:73], s[20:21]
	v_lshl_add_u64 v[10:11], v[10:11], 2, s[76:77]
	v_mad_i64_i32 v[74:75], s[14:15], v216, s10, v[72:73]
	v_mad_i64_i32 v[72:73], s[14:15], v9, s10, v[72:73]
	v_readlane_b32 s72, v249, 16
	v_lshl_add_u64 v[74:75], v[74:75], 0, s[22:23]
	v_lshl_add_u64 v[72:73], v[72:73], 0, s[22:23]
	v_lshl_add_u64 v[74:75], v[74:75], 0, v[198:199]
	v_lshl_add_u64 v[72:73], v[72:73], 0, v[198:199]
	global_load_dword v218, v[10:11], off
	global_load_dwordx4 v[84:87], v[74:75], off offset:1024
	global_load_dwordx4 v[80:83], v[74:75], off offset:1088
	s_nop 0
	global_load_dword v10, v[10:11], off offset:64
	s_nop 0
	global_load_dwordx4 v[76:79], v[72:73], off offset:1024
	s_nop 0
	global_load_dwordx4 v[72:75], v[72:73], off offset:1088
	s_waitcnt vmcnt(23)
	v_lshlrev_b32_e32 v9, 16, v68
	v_and_b32_e32 v11, 0xffff0000, v68
	v_lshl_add_u64 v[220:221], v[220:221], 1, s[24:25]
	v_readlane_b32 s73, v249, 17
	v_readlane_b32 s74, v249, 18
	v_readlane_b32 s75, v249, 19
	v_readlane_b32 s76, v249, 20
	v_readlane_b32 s77, v249, 21
	v_readlane_b32 s78, v249, 22
	v_readlane_b32 s79, v249, 23
	v_readlane_b32 s80, v249, 24
	v_readlane_b32 s81, v249, 25
	v_readlane_b32 s82, v249, 26
	v_readlane_b32 s83, v249, 27
	v_readlane_b32 s84, v249, 28
	v_readlane_b32 s85, v249, 29
	v_readlane_b32 s72, v249, 0
	v_readlane_b32 s84, v249, 12
	v_readlane_b32 s85, v249, 13
	v_readlane_b32 s86, v249, 14
	v_readlane_b32 s87, v249, 15
	s_mov_b64 s[28:29], s[84:85]
	v_readlane_b32 s80, v249, 8
	v_readlane_b32 s81, v249, 9
	v_readlane_b32 s82, v249, 10
	v_readlane_b32 s83, v249, 11
	s_mov_b64 s[80:81], s[88:89]
	s_andn2_b64 vcc, exec, s[0:1]
	s_mov_b64 s[82:83], s[90:91]
	v_readlane_b32 s73, v249, 1
	v_readlane_b32 s74, v249, 2
	v_readlane_b32 s75, v249, 3
	v_readlane_b32 s76, v249, 4
	v_readlane_b32 s77, v249, 5
	v_readlane_b32 s78, v249, 6
	v_readlane_b32 s79, v249, 7
	s_mov_b64 s[30:31], s[86:87]
	s_waitcnt vmcnt(15)
	v_pk_mul_f32 v[184:185], v[184:185], v[176:177]
	s_waitcnt vmcnt(14)
	v_pk_mul_f32 v[188:189], v[188:189], v[180:181]
	v_pk_mul_f32 v[190:191], v[190:191], v[182:183]
	v_mul_f32_e32 v9, v188, v9
	v_mul_f32_e32 v11, v189, v11
	v_cvt_pk_bf16_f32 v68, v9, v11
	v_lshlrev_b32_e32 v9, 16, v69
	v_and_b32_e32 v11, 0xffff0000, v69
	v_mul_f32_e32 v9, v190, v9
	v_mul_f32_e32 v11, v191, v11
	v_cvt_pk_bf16_f32 v69, v9, v11
	v_lshlrev_b32_e32 v9, 16, v70
	v_and_b32_e32 v11, 0xffff0000, v70
	v_mul_f32_e32 v9, v184, v9
	v_mul_f32_e32 v11, v185, v11
	v_pk_mul_f32 v[186:187], v[186:187], v[178:179]
	v_cvt_pk_bf16_f32 v70, v9, v11
	v_lshlrev_b32_e32 v9, 16, v71
	v_and_b32_e32 v11, 0xffff0000, v71
	v_lshlrev_b64 v[184:185], 11, v[214:215]
	v_mul_f32_e32 v9, v186, v9
	v_mul_f32_e32 v11, v187, v11
	v_cvt_pk_bf16_f32 v71, v9, v11
	v_lshl_add_u64 v[184:185], v[220:221], 0, v[184:185]
	global_store_dwordx4 v[184:185], v[68:71], off
	v_lshlrev_b32_e32 v9, 16, v64
	v_and_b32_e32 v11, 0xffff0000, v64
	v_pk_mul_f32 v[70:71], v[172:173], v[180:181]
	v_pk_mul_f32 v[68:69], v[174:175], v[182:183]
	v_mul_f32_e32 v9, v70, v9
	v_mul_f32_e32 v11, v71, v11
	v_cvt_pk_bf16_f32 v64, v9, v11
	v_lshlrev_b32_e32 v9, 16, v65
	v_and_b32_e32 v11, 0xffff0000, v65
	v_mul_f32_e32 v9, v68, v9
	v_mul_f32_e32 v11, v69, v11
	v_pk_mul_f32 v[168:169], v[168:169], v[176:177]
	v_cvt_pk_bf16_f32 v65, v9, v11
	v_lshlrev_b32_e32 v9, 16, v66
	v_and_b32_e32 v11, 0xffff0000, v66
	v_mul_f32_e32 v9, v168, v9
	v_mul_f32_e32 v11, v169, v11
	v_pk_mul_f32 v[170:171], v[170:171], v[178:179]
	v_cvt_pk_bf16_f32 v66, v9, v11
	v_lshlrev_b32_e32 v9, 16, v67
	v_and_b32_e32 v11, 0xffff0000, v67
	v_lshlrev_b64 v[68:69], 11, v[212:213]
	v_mul_f32_e32 v9, v170, v9
	v_mul_f32_e32 v11, v171, v11
	v_cvt_pk_bf16_f32 v67, v9, v11
	v_lshl_add_u64 v[68:69], v[220:221], 0, v[68:69]
	global_store_dwordx4 v[68:69], v[64:67], off
	v_lshlrev_b32_e32 v9, 16, v60
	v_and_b32_e32 v11, 0xffff0000, v60
	v_pk_mul_f32 v[66:67], v[164:165], v[180:181]
	v_pk_mul_f32 v[64:65], v[166:167], v[182:183]
	v_mul_f32_e32 v9, v66, v9
	v_mul_f32_e32 v11, v67, v11
	v_cvt_pk_bf16_f32 v60, v9, v11
	v_lshlrev_b32_e32 v9, 16, v61
	v_and_b32_e32 v11, 0xffff0000, v61
	v_mul_f32_e32 v9, v64, v9
	v_mul_f32_e32 v11, v65, v11
	v_pk_mul_f32 v[70:71], v[160:161], v[176:177]
	v_cvt_pk_bf16_f32 v61, v9, v11
	v_lshlrev_b32_e32 v9, 16, v62
	v_and_b32_e32 v11, 0xffff0000, v62
	v_mul_f32_e32 v9, v70, v9
	v_mul_f32_e32 v11, v71, v11
	v_pk_mul_f32 v[68:69], v[162:163], v[178:179]
	v_cvt_pk_bf16_f32 v62, v9, v11
	v_lshlrev_b32_e32 v9, 16, v63
	v_and_b32_e32 v11, 0xffff0000, v63
	v_lshlrev_b64 v[64:65], 11, v[210:211]
	v_mul_f32_e32 v9, v68, v9
	v_mul_f32_e32 v11, v69, v11
	v_cvt_pk_bf16_f32 v63, v9, v11
	v_lshl_add_u64 v[64:65], v[220:221], 0, v[64:65]
	global_store_dwordx4 v[64:65], v[60:63], off
	v_lshlrev_b32_e32 v9, 16, v56
	v_and_b32_e32 v11, 0xffff0000, v56
	v_pk_mul_f32 v[62:63], v[156:157], v[180:181]
	v_pk_mul_f32 v[60:61], v[158:159], v[182:183]
	v_mul_f32_e32 v9, v62, v9
	v_mul_f32_e32 v11, v63, v11
	v_cvt_pk_bf16_f32 v56, v9, v11
	v_lshlrev_b32_e32 v9, 16, v57
	v_and_b32_e32 v11, 0xffff0000, v57
	v_mul_f32_e32 v9, v60, v9
	v_mul_f32_e32 v11, v61, v11
	v_pk_mul_f32 v[66:67], v[152:153], v[176:177]
	v_cvt_pk_bf16_f32 v57, v9, v11
	v_lshlrev_b32_e32 v9, 16, v58
	v_and_b32_e32 v11, 0xffff0000, v58
	v_mul_f32_e32 v9, v66, v9
	v_mul_f32_e32 v11, v67, v11
	v_pk_mul_f32 v[64:65], v[154:155], v[178:179]
	v_cvt_pk_bf16_f32 v58, v9, v11
	v_lshlrev_b32_e32 v9, 16, v59
	v_and_b32_e32 v11, 0xffff0000, v59
	v_lshlrev_b64 v[60:61], 11, v[208:209]
	v_mul_f32_e32 v9, v64, v9
	v_mul_f32_e32 v11, v65, v11
	v_cvt_pk_bf16_f32 v59, v9, v11
	v_lshl_add_u64 v[60:61], v[220:221], 0, v[60:61]
	global_store_dwordx4 v[60:61], v[56:59], off
	v_lshlrev_b32_e32 v9, 16, v52
	v_and_b32_e32 v11, 0xffff0000, v52
	v_pk_mul_f32 v[58:59], v[148:149], v[180:181]
	v_pk_mul_f32 v[56:57], v[150:151], v[182:183]
	v_mul_f32_e32 v9, v58, v9
	v_mul_f32_e32 v11, v59, v11
	v_cvt_pk_bf16_f32 v52, v9, v11
	v_lshlrev_b32_e32 v9, 16, v53
	v_and_b32_e32 v11, 0xffff0000, v53
	v_mul_f32_e32 v9, v56, v9
	v_mul_f32_e32 v11, v57, v11
	v_pk_mul_f32 v[62:63], v[144:145], v[176:177]
	v_cvt_pk_bf16_f32 v53, v9, v11
	v_lshlrev_b32_e32 v9, 16, v54
	v_and_b32_e32 v11, 0xffff0000, v54
	v_mul_f32_e32 v9, v62, v9
	v_mul_f32_e32 v11, v63, v11
	v_pk_mul_f32 v[60:61], v[146:147], v[178:179]
	v_cvt_pk_bf16_f32 v54, v9, v11
	v_lshlrev_b32_e32 v9, 16, v55
	v_and_b32_e32 v11, 0xffff0000, v55
	v_lshlrev_b64 v[56:57], 11, v[206:207]
	v_mul_f32_e32 v9, v60, v9
	v_mul_f32_e32 v11, v61, v11
	v_cvt_pk_bf16_f32 v55, v9, v11
	v_lshl_add_u64 v[56:57], v[220:221], 0, v[56:57]
	global_store_dwordx4 v[56:57], v[52:55], off
	v_lshlrev_b32_e32 v9, 16, v48
	v_and_b32_e32 v11, 0xffff0000, v48
	v_pk_mul_f32 v[54:55], v[140:141], v[180:181]
	v_pk_mul_f32 v[52:53], v[142:143], v[182:183]
	v_mul_f32_e32 v9, v54, v9
	v_mul_f32_e32 v11, v55, v11
	v_cvt_pk_bf16_f32 v48, v9, v11
	v_lshlrev_b32_e32 v9, 16, v49
	v_and_b32_e32 v11, 0xffff0000, v49
	v_mul_f32_e32 v9, v52, v9
	v_mul_f32_e32 v11, v53, v11
	v_pk_mul_f32 v[58:59], v[136:137], v[176:177]
	v_cvt_pk_bf16_f32 v49, v9, v11
	v_lshlrev_b32_e32 v9, 16, v50
	v_and_b32_e32 v11, 0xffff0000, v50
	v_mul_f32_e32 v9, v58, v9
	v_mul_f32_e32 v11, v59, v11
	v_pk_mul_f32 v[56:57], v[138:139], v[178:179]
	v_cvt_pk_bf16_f32 v50, v9, v11
	v_lshlrev_b32_e32 v9, 16, v51
	v_and_b32_e32 v11, 0xffff0000, v51
	v_lshlrev_b64 v[52:53], 11, v[204:205]
	v_mul_f32_e32 v9, v56, v9
	v_mul_f32_e32 v11, v57, v11
	v_cvt_pk_bf16_f32 v51, v9, v11
	v_lshl_add_u64 v[52:53], v[220:221], 0, v[52:53]
	global_store_dwordx4 v[52:53], v[48:51], off
	v_lshlrev_b32_e32 v9, 16, v44
	v_and_b32_e32 v11, 0xffff0000, v44
	v_pk_mul_f32 v[50:51], v[132:133], v[180:181]
	v_pk_mul_f32 v[48:49], v[134:135], v[182:183]
	v_mul_f32_e32 v9, v50, v9
	v_mul_f32_e32 v11, v51, v11
	v_cvt_pk_bf16_f32 v44, v9, v11
	v_lshlrev_b32_e32 v9, 16, v45
	v_and_b32_e32 v11, 0xffff0000, v45
	v_mul_f32_e32 v9, v48, v9
	v_mul_f32_e32 v11, v49, v11
	v_pk_mul_f32 v[54:55], v[128:129], v[176:177]
	v_cvt_pk_bf16_f32 v45, v9, v11
	v_lshlrev_b32_e32 v9, 16, v46
	v_and_b32_e32 v11, 0xffff0000, v46
	v_mul_f32_e32 v9, v54, v9
	v_mul_f32_e32 v11, v55, v11
	v_pk_mul_f32 v[52:53], v[130:131], v[178:179]
	v_cvt_pk_bf16_f32 v46, v9, v11
	v_lshlrev_b32_e32 v9, 16, v47
	v_and_b32_e32 v11, 0xffff0000, v47
	v_lshlrev_b64 v[48:49], 11, v[202:203]
	v_mul_f32_e32 v9, v52, v9
	v_mul_f32_e32 v11, v53, v11
	v_cvt_pk_bf16_f32 v47, v9, v11
	v_lshl_add_u64 v[48:49], v[220:221], 0, v[48:49]
	global_store_dwordx4 v[48:49], v[44:47], off
	v_lshlrev_b32_e32 v9, 16, v40
	v_and_b32_e32 v11, 0xffff0000, v40
	v_pk_mul_f32 v[46:47], v[124:125], v[180:181]
	v_pk_mul_f32 v[44:45], v[126:127], v[182:183]
	v_mul_f32_e32 v9, v46, v9
	v_mul_f32_e32 v11, v47, v11
	v_cvt_pk_bf16_f32 v40, v9, v11
	v_lshlrev_b32_e32 v9, 16, v41
	v_and_b32_e32 v11, 0xffff0000, v41
	v_mul_f32_e32 v9, v44, v9
	v_mul_f32_e32 v11, v45, v11
	v_pk_mul_f32 v[50:51], v[120:121], v[176:177]
	v_cvt_pk_bf16_f32 v41, v9, v11
	v_lshlrev_b32_e32 v9, 16, v42
	v_and_b32_e32 v11, 0xffff0000, v42
	v_mul_f32_e32 v9, v50, v9
	v_mul_f32_e32 v11, v51, v11
	v_pk_mul_f32 v[48:49], v[122:123], v[178:179]
	v_cvt_pk_bf16_f32 v42, v9, v11
	v_lshlrev_b32_e32 v9, 16, v43
	v_and_b32_e32 v11, 0xffff0000, v43
	v_lshlrev_b64 v[44:45], 11, v[200:201]
	v_mul_f32_e32 v9, v48, v9
	v_mul_f32_e32 v11, v49, v11
	v_cvt_pk_bf16_f32 v43, v9, v11
	v_lshl_add_u64 v[44:45], v[220:221], 0, v[44:45]
	global_store_dwordx4 v[44:45], v[40:43], off
	ds_read_b128 v[40:43], v244
	ds_read_b128 v[48:51], v244 offset:64
	s_waitcnt lgkmcnt(1)
	s_waitcnt vmcnt(8)
	v_mfma_f32_16x16x32_bf16 v[44:47], v[40:43], v[112:115], 0
	ds_read_b128 v[56:59], v244 offset:1152
	ds_read_b128 v[64:67], v244 offset:8768
	v_lshlrev_b32_e32 v9, 16, v84
	v_mfma_f32_16x16x32_bf16 v[40:43], v[40:43], v[116:119], 0
	v_and_b32_e32 v11, 0xffff0000, v84
	s_waitcnt lgkmcnt(2)
	v_mfma_f32_16x16x32_bf16 v[44:47], v[48:51], v[100:103], v[44:47]
	v_mfma_f32_16x16x32_bf16 v[40:43], v[48:51], v[108:111], v[40:43]
	ds_read_b128 v[48:51], v244 offset:128
	s_waitcnt lgkmcnt(0)
	v_mfma_f32_16x16x32_bf16 v[44:47], v[48:51], v[96:99], v[44:47]
	v_mfma_f32_16x16x32_bf16 v[40:43], v[48:51], v[104:107], v[40:43]
	ds_read_b128 v[48:51], v244 offset:192
	s_waitcnt lgkmcnt(0)
	v_mfma_f32_16x16x32_bf16 v[44:47], v[48:51], v[92:95], v[44:47]
	s_nop 7
	v_pk_add_f32 v[44:45], v[218:219], v[44:45] op_sel_hi:[0,1]
	v_mfma_f32_16x16x32_bf16 v[40:43], v[48:51], v[88:91], v[40:43]
	ds_read_b128 v[48:51], v244 offset:1088
	v_mul_f32_e32 v9, v44, v9
	v_mul_f32_e32 v11, v45, v11
	s_waitcnt lgkmcnt(0)
	v_mfma_f32_16x16x32_bf16 v[52:55], v[48:51], v[112:115], 0
	v_add_f32_e64 v46, v218, v46
	v_add_f32_e64 v47, v218, v47
	v_mfma_f32_16x16x32_bf16 v[48:51], v[48:51], v[116:119], 0
	v_mfma_f32_16x16x32_bf16 v[52:55], v[56:59], v[100:103], v[52:55]
	v_mfma_f32_16x16x32_bf16 v[48:51], v[56:59], v[108:111], v[48:51]
	ds_read_b128 v[56:59], v244 offset:1216
	s_waitcnt lgkmcnt(0)
	v_mfma_f32_16x16x32_bf16 v[52:55], v[56:59], v[96:99], v[52:55]
	v_mfma_f32_16x16x32_bf16 v[48:51], v[56:59], v[104:107], v[48:51]
	ds_read_b128 v[56:59], v244 offset:1280
	s_waitcnt lgkmcnt(0)
	v_mfma_f32_16x16x32_bf16 v[52:55], v[56:59], v[92:95], v[52:55]
	s_nop 7
	v_pk_add_f32 v[52:53], v[218:219], v[52:53] op_sel_hi:[0,1]
	v_mfma_f32_16x16x32_bf16 v[48:51], v[56:59], v[88:91], v[48:51]
	ds_read_b128 v[56:59], v244 offset:8704
	v_pk_add_f32 v[54:55], v[218:219], v[54:55] op_sel_hi:[0,1]
	s_waitcnt lgkmcnt(0)
	v_mfma_f32_16x16x32_bf16 v[60:63], v[56:59], v[112:115], 0
	v_mfma_f32_16x16x32_bf16 v[56:59], v[56:59], v[116:119], 0
	v_mfma_f32_16x16x32_bf16 v[60:63], v[64:67], v[100:103], v[60:63]
	v_mfma_f32_16x16x32_bf16 v[56:59], v[64:67], v[108:111], v[56:59]
	ds_read_b128 v[64:67], v244 offset:8832
	s_waitcnt lgkmcnt(0)
	v_mfma_f32_16x16x32_bf16 v[60:63], v[64:67], v[96:99], v[60:63]
	v_mfma_f32_16x16x32_bf16 v[56:59], v[64:67], v[104:107], v[56:59]
	ds_read_b128 v[64:67], v244 offset:8896
	s_waitcnt lgkmcnt(0)
	v_mfma_f32_16x16x32_bf16 v[60:63], v[64:67], v[92:95], v[60:63]
	v_mfma_f32_16x16x32_bf16 v[56:59], v[64:67], v[88:91], v[56:59]
	ds_read_b128 v[64:67], v244 offset:9792
	s_waitcnt lgkmcnt(0)
	v_mfma_f32_16x16x32_bf16 v[68:71], v[64:67], v[112:115], 0
	ds_read_b128 v[112:115], v244 offset:9856
	s_waitcnt lgkmcnt(0)
	v_mfma_f32_16x16x32_bf16 v[68:71], v[112:115], v[100:103], v[68:71]
	ds_read_b128 v[100:103], v244 offset:9920
	v_mfma_f32_16x16x32_bf16 v[64:67], v[64:67], v[116:119], 0
	s_waitcnt lgkmcnt(0)
	v_mfma_f32_16x16x32_bf16 v[68:71], v[100:103], v[96:99], v[68:71]
	ds_read_b128 v[96:99], v244 offset:9984
	v_cvt_pk_bf16_f32 v44, v9, v11
	v_lshlrev_b32_e32 v9, 16, v85
	v_mfma_f32_16x16x32_bf16 v[64:67], v[112:115], v[108:111], v[64:67]
	v_and_b32_e32 v11, 0xffff0000, v85
	v_mul_f32_e32 v9, v46, v9
	v_mul_f32_e32 v11, v47, v11
	v_mfma_f32_16x16x32_bf16 v[64:67], v[100:103], v[104:107], v[64:67]
	v_cvt_pk_bf16_f32 v45, v9, v11
	v_lshlrev_b32_e32 v9, 16, v86
	v_and_b32_e32 v11, 0xffff0000, v86
	s_waitcnt lgkmcnt(0)
	v_mfma_f32_16x16x32_bf16 v[64:67], v[96:99], v[88:91], v[64:67]
	v_lshlrev_b64 v[88:89], 10, v[216:217]
	v_mul_f32_e32 v9, v52, v9
	v_mul_f32_e32 v11, v53, v11
	v_lshl_add_u64 v[88:89], s[28:29], 0, v[88:89]
	v_cvt_pk_bf16_f32 v46, v9, v11
	v_lshlrev_b32_e32 v9, 16, v87
	v_and_b32_e32 v11, 0xffff0000, v87
	v_or_b32_e32 v52, s22, v198
	v_mov_b32_e32 v53, v8
	v_mul_f32_e32 v9, v54, v9
	v_mul_f32_e32 v11, v55, v11
	v_lshl_add_u64 v[54:55], v[88:89], 0, v[52:53]
	v_mfma_f32_16x16x32_bf16 v[68:71], v[96:99], v[92:95], v[68:71]
	v_cvt_pk_bf16_f32 v47, v9, v11
	global_store_dwordx4 v[54:55], v[44:47], off
	v_lshlrev_b32_e32 v9, 16, v80
	v_and_b32_e32 v11, 0xffff0000, v80
	v_pk_add_f32 v[44:45], v[218:219], v[60:61] op_sel_hi:[0,1]
	v_mul_f32_e32 v9, v44, v9
	v_mul_f32_e32 v11, v45, v11
	v_pk_add_f32 v[46:47], v[218:219], v[62:63] op_sel_hi:[0,1]
	v_cvt_pk_bf16_f32 v44, v9, v11
	v_lshlrev_b32_e32 v9, 16, v81
	v_and_b32_e32 v11, 0xffff0000, v81
	v_mul_f32_e32 v9, v46, v9
	v_mul_f32_e32 v11, v47, v11
	v_pk_add_f32 v[62:63], v[218:219], v[68:69] op_sel_hi:[0,1]
	v_cvt_pk_bf16_f32 v45, v9, v11
	v_lshlrev_b32_e32 v9, 16, v82
	v_and_b32_e32 v11, 0xffff0000, v82
	v_mul_f32_e32 v9, v62, v9
	v_mul_f32_e32 v11, v63, v11
	v_pk_add_f32 v[60:61], v[218:219], v[70:71] op_sel_hi:[0,1]
	v_cvt_pk_bf16_f32 v46, v9, v11
	v_lshlrev_b32_e32 v9, 16, v83
	v_and_b32_e32 v11, 0xffff0000, v83
	v_mul_f32_e32 v9, v60, v9
	v_mul_f32_e32 v11, v61, v11
	v_cvt_pk_bf16_f32 v47, v9, v11
	global_store_dwordx4 v[54:55], v[44:47], off offset:64
	v_pk_add_f32 v[42:43], v[10:11], v[42:43] op_sel_hi:[0,1]
	v_pk_add_f32 v[40:41], v[10:11], v[40:41] op_sel_hi:[0,1]
	v_pk_add_f32 v[46:47], v[10:11], v[50:51] op_sel_hi:[0,1]
	v_pk_add_f32 v[48:49], v[10:11], v[48:49] op_sel_hi:[0,1]
	v_lshlrev_b32_e32 v9, 16, v76
	v_and_b32_e32 v11, 0xffff0000, v76
	v_mul_f32_e32 v9, v40, v9
	v_mul_f32_e32 v11, v41, v11
	v_cvt_pk_bf16_f32 v40, v9, v11
	v_lshlrev_b32_e32 v9, 16, v77
	v_and_b32_e32 v11, 0xffff0000, v77
	v_or_b32_e32 v44, 16, v216
	v_mul_f32_e32 v9, v42, v9
	v_mul_f32_e32 v11, v43, v11
	v_ashrrev_i32_e32 v45, 31, v44
	v_cvt_pk_bf16_f32 v41, v9, v11
	v_lshlrev_b32_e32 v9, 16, v78
	v_and_b32_e32 v11, 0xffff0000, v78
	v_lshlrev_b64 v[44:45], 10, v[44:45]
	v_mul_f32_e32 v9, v48, v9
	v_mul_f32_e32 v11, v49, v11
	v_lshl_add_u64 v[44:45], s[28:29], 0, v[44:45]
	v_cvt_pk_bf16_f32 v42, v9, v11
	v_lshlrev_b32_e32 v9, 16, v79
	v_and_b32_e32 v11, 0xffff0000, v79
	v_mul_f32_e32 v9, v46, v9
	v_mul_f32_e32 v11, v47, v11
	v_lshl_add_u64 v[44:45], v[44:45], 0, v[52:53]
	v_cvt_pk_bf16_f32 v43, v9, v11
	global_store_dwordx4 v[44:45], v[40:43], off
	v_lshlrev_b32_e32 v9, 16, v72
	v_pk_add_f32 v[46:47], v[10:11], v[66:67] op_sel_hi:[0,1]
	v_pk_add_f32 v[40:41], v[10:11], v[56:57] op_sel_hi:[0,1]
	v_mul_f32_e32 v9, v40, v9
	v_and_b32_e32 v40, 0xffff0000, v72
	v_mul_f32_e32 v40, v41, v40
	v_pk_add_f32 v[42:43], v[10:11], v[58:59] op_sel_hi:[0,1]
	v_cvt_pk_bf16_f32 v40, v9, v40
	v_lshlrev_b32_e32 v9, 16, v73
	v_and_b32_e32 v41, 0xffff0000, v73
	v_mul_f32_e32 v9, v42, v9
	v_mul_f32_e32 v41, v43, v41
	v_pk_add_f32 v[10:11], v[10:11], v[64:65] op_sel_hi:[0,1]
	v_cvt_pk_bf16_f32 v41, v9, v41
	v_lshlrev_b32_e32 v9, 16, v74
	v_mul_f32_e32 v9, v10, v9
	v_and_b32_e32 v10, 0xffff0000, v74
	v_mul_f32_e32 v10, v11, v10
	v_cvt_pk_bf16_f32 v42, v9, v10
	v_lshlrev_b32_e32 v9, 16, v75
	v_and_b32_e32 v10, 0xffff0000, v75
	v_mul_f32_e32 v9, v46, v9
	v_mul_f32_e32 v10, v47, v10
	v_cvt_pk_bf16_f32 v43, v9, v10
	global_store_dwordx4 v[44:45], v[40:43], off offset:64
	s_barrier
	s_cbranch_vccz .LBB0_329
